# branch-GEMM epilogue: gate loads for 6 of 7 later row groups issued up front; per-group full waits on stores removed
# speedup vs baseline: 1.0186x; 1.0047x over previous
; __device__ __forceinline__ unsigned pk2(float lo, float hi) { f32x2 v = {lo, hi}; bf16x2_t b = __builtin_convertvector(v, bf16x2_t); return __builtin_bit_cast(unsigned, b); }
;     static __device__ __forceinline__ void unpack8(u32x4 w, f32x4& a, f32x4& b) { a = (f32x4){::bflo(w.x), ::bfhi(w.x), ::bflo(w.y), ::bfhi(w.y)}; b = (f32x4){::bflo(w.z), ::bfhi(w.z), ::bflo(w.w), ::bfhi(w.w)}; }
;     __device__ __forceinline__ void operator()(const f32x4 (&acc)[2][2][4][2], const Unit& u, int wr, int wc, int fr, int fq) const {
;         const int row0 = u.pm * BM + wr * 64 + fr, col0 = u.pn * BM + wc * 32 + 8 * fq;
; #pragma unroll
;         for (int ai = 0; ai < 2; ++ai)
; #pragma unroll
;             for (int m = 0; m < 4; ++m) {
;                 const size_t r = (size_t)(row0 + ai * HALF + m * 16);
;                 u32x4 gv[2];
; #pragma unroll
;                 for (int bj = 0; bj < 2; ++bj) gv[bj] = *(const u32x4*)(G + r * 3072 + 2048 + col0 + bj * HALF);
; #pragma unroll
;                 for (int bj = 0; bj < 2; ++bj) {
;                     f32x4 g0, g1; unpack8(gv[bj], g0, g1);
;                     f32x4 v0 = acc[ai][bj][m][0], v1 = acc[ai][bj][m][1];
; #pragma unroll
;                     for (int j = 0; j < 4; ++j) { v0[j] *= fmaxf(g0[j], 1e-30f); v1[j] *= fmaxf(g1[j], 1e-30f); }
;                     u32x4 w; w.x = ::pk2(v0[0], v0[1]); w.y = ::pk2(v0[2], v0[3]); w.z = ::pk2(v1[0], v1[1]); w.w = ::pk2(v1[2], v1[3]);
;                     *(u32x4*)(Bo + r * 1024 + col0 + bj * HALF) = w;
;                 }
.LBB0_146:
	v_mov_b64_e32 v[148:149], s[72:73]
	v_mad_i64_i32 v[140:141], s[14:15], v144, s4, v[148:149]
	v_lshlrev_b64 v[0:1], 1, v[146:147]
	v_lshl_add_u64 v[140:141], v[140:141], 0, v[0:1]
	v_add_co_u32_e32 v146, vcc, s2, v140
	s_mov_b64 s[54:55], 0x1000
	s_nop 0
	v_addc_co_u32_e32 v147, vcc, 0, v141, vcc
	global_load_dwordx4 v[150:153], v[146:147], off
	v_lshl_add_u64 v[140:141], v[140:141], 0, s[54:55]
	global_load_dwordx4 v[154:157], v[140:141], off offset:256
	v_or_b32_e32 v252, 16, v144
	v_mad_i64_i32 v[236:237], s[14:15], v252, s4, v[148:149]
	v_lshl_add_u64 v[236:237], v[236:237], 0, v[0:1]
	v_lshl_add_u64 v[236:237], v[236:237], 0, s[54:55]
	global_load_dwordx4 v[196:199], v[236:237], off
	global_load_dwordx4 v[200:203], v[236:237], off offset:256
	v_or_b32_e32 v252, 32, v144
	v_mad_i64_i32 v[236:237], s[14:15], v252, s4, v[148:149]
	v_lshl_add_u64 v[236:237], v[236:237], 0, v[0:1]
	v_lshl_add_u64 v[236:237], v[236:237], 0, s[54:55]
	global_load_dwordx4 v[204:207], v[236:237], off
	global_load_dwordx4 v[208:211], v[236:237], off offset:256
	v_or_b32_e32 v252, 48, v144
	v_mad_i64_i32 v[236:237], s[14:15], v252, s4, v[148:149]
	v_lshl_add_u64 v[236:237], v[236:237], 0, v[0:1]
	v_lshl_add_u64 v[236:237], v[236:237], 0, s[54:55]
	global_load_dwordx4 v[212:215], v[236:237], off
	global_load_dwordx4 v[216:219], v[236:237], off offset:256
	v_add_u32_e32 v252, 128, v144
	v_mad_i64_i32 v[236:237], s[14:15], v252, s4, v[148:149]
	v_lshl_add_u64 v[236:237], v[236:237], 0, v[0:1]
	v_lshl_add_u64 v[236:237], v[236:237], 0, s[54:55]
	global_load_dwordx4 v[220:223], v[236:237], off
	global_load_dwordx4 v[224:227], v[236:237], off offset:256
	v_add_u32_e32 v252, 144, v144
	v_mad_i64_i32 v[236:237], s[14:15], v252, s4, v[148:149]
	v_lshl_add_u64 v[236:237], v[236:237], 0, v[0:1]
	v_lshl_add_u64 v[236:237], v[236:237], 0, s[54:55]
	global_load_dwordx4 v[228:231], v[236:237], off
	global_load_dwordx4 v[232:235], v[236:237], off offset:256
	v_add_u32_e32 v252, 160, v144
	v_mad_i64_i32 v[236:237], s[14:15], v252, s4, v[148:149]
	v_lshl_add_u64 v[236:237], v[236:237], 0, v[0:1]
	v_lshl_add_u64 v[236:237], v[236:237], 0, s[54:55]
	global_load_dwordx4 v[240:243], v[236:237], off
	global_load_dwordx4 v[244:247], v[236:237], off offset:256
	v_ashrrev_i32_e32 v145, 31, v144
	v_lshlrev_b64 v[140:141], 11, v[144:145]
	v_or_b32_e32 v146, 16, v144
	v_mad_i64_i32 v[158:159], s[14:15], v146, s4, v[148:149]
	v_lshl_add_u64 v[140:141], s[46:47], 0, v[140:141]
	v_lshl_add_u64 v[158:159], v[158:159], 0, v[0:1]
	v_lshl_add_u64 v[140:141], v[140:141], 0, v[0:1]
	v_lshl_add_u64 v[160:161], v[158:159], 0, s[54:55]
	v_add_co_u32_e32 v158, vcc, s2, v158
	v_mov_b64_e32 v[238:239], v[142:143]
	s_nop 0
	v_addc_co_u32_e32 v159, vcc, 0, v159, vcc
	s_waitcnt vmcnt(0)
	v_lshlrev_b32_e32 v3, 16, v150
	v_and_b32_e32 v145, 0xffff0000, v150
	v_lshlrev_b32_e32 v147, 16, v151
	v_and_b32_e32 v150, 0xffff0000, v151
	v_lshlrev_b32_e32 v151, 16, v152
	v_and_b32_e32 v152, 0xffff0000, v152
	v_lshlrev_b32_e32 v162, 16, v153
	v_and_b32_e32 v153, 0xffff0000, v153
	v_lshlrev_b32_e32 v163, 16, v154
	v_and_b32_e32 v154, 0xffff0000, v154
	v_lshlrev_b32_e32 v172, 16, v155
	v_and_b32_e32 v155, 0xffff0000, v155
	v_lshlrev_b32_e32 v173, 16, v156
	v_and_b32_e32 v156, 0xffff0000, v156
	v_lshlrev_b32_e32 v184, 16, v157
	v_and_b32_e32 v157, 0xffff0000, v157
	v_max_f32_e32 v3, v3, v3
	v_max_f32_e32 v151, v151, v151
	v_max_f32_e32 v145, v145, v145
	v_max_f32_e32 v185, v152, v152
	v_max_f32_e32 v147, v147, v147
	v_max_f32_e32 v162, v162, v162
	v_max_f32_e32 v188, v150, v150
	v_max_f32_e32 v189, v153, v153
	v_max_f32_e32 v163, v163, v163
	v_max_f32_e32 v173, v173, v173
	v_max_f32_e32 v190, v154, v154
	v_max_f32_e32 v191, v156, v156
	v_max_f32_e32 v192, v172, v172
	v_max_f32_e32 v193, v184, v184
	v_max_f32_e32 v194, v155, v155
	v_max_f32_e32 v195, v157, v157
	v_max_f32_e32 v150, 0xda24260, v3
	v_max_f32_e32 v152, 0xda24260, v151
	v_max_f32_e32 v151, 0xda24260, v145
	v_max_f32_e32 v153, 0xda24260, v185
	v_max_f32_e32 v154, 0xda24260, v147
	v_max_f32_e32 v156, 0xda24260, v162
	v_max_f32_e32 v155, 0xda24260, v188
	v_max_f32_e32 v157, 0xda24260, v189
	v_max_f32_e32 v162, 0xda24260, v163
	v_max_f32_e32 v172, 0xda24260, v173
	v_max_f32_e32 v163, 0xda24260, v190
	v_max_f32_e32 v173, 0xda24260, v191
	v_max_f32_e32 v184, 0xda24260, v192
	v_max_f32_e32 v188, 0xda24260, v193
	v_max_f32_e32 v185, 0xda24260, v194
	v_max_f32_e32 v189, 0xda24260, v195
	v_pk_mul_f32 v[128:129], v[128:129], v[150:151]
	v_pk_mul_f32 v[150:151], v[124:125], v[152:153]
	v_pk_mul_f32 v[130:131], v[130:131], v[154:155]
	v_pk_mul_f32 v[152:153], v[126:127], v[156:157]
	v_pk_mul_f32 v[120:121], v[120:121], v[162:163]
	v_pk_mul_f32 v[154:155], v[116:117], v[172:173]
	v_cvt_pk_bf16_f32 v124, v128, v129
	v_cvt_pk_bf16_f32 v125, v130, v131
	v_cvt_pk_bf16_f32 v126, v150, v151
	v_cvt_pk_bf16_f32 v127, v152, v153
	v_pk_mul_f32 v[122:123], v[122:123], v[184:185]
	v_pk_mul_f32 v[128:129], v[118:119], v[188:189]
	global_store_dwordx4 v[140:141], v[124:127], off sc1
	v_cvt_pk_bf16_f32 v116, v120, v121
	v_cvt_pk_bf16_f32 v117, v122, v123
	v_cvt_pk_bf16_f32 v118, v154, v155
	v_cvt_pk_bf16_f32 v119, v128, v129
	s_nop 1
	v_mov_b32_e32 v124, v196
	v_mov_b32_e32 v125, v197
	v_mov_b32_e32 v126, v198
	v_mov_b32_e32 v127, v199
	v_ashrrev_i32_e32 v147, 31, v146
	global_store_dwordx4 v[140:141], v[116:119], off offset:256 sc1
	s_nop 1
	v_mov_b32_e32 v118, v200
	v_mov_b32_e32 v119, v201
	v_mov_b32_e32 v120, v202
	v_mov_b32_e32 v121, v203
	v_lshlrev_b64 v[128:129], 11, v[146:147]
	v_or_b32_e32 v116, 32, v144
	v_mad_i64_i32 v[122:123], s[14:15], v116, s4, v[148:149]
; __device__ __forceinline__ unsigned pk2(float lo, float hi) { f32x2 v = {lo, hi}; bf16x2_t b = __builtin_convertvector(v, bf16x2_t); return __builtin_bit_cast(unsigned, b); }
;     static __device__ __forceinline__ void unpack8(u32x4 w, f32x4& a, f32x4& b) { a = (f32x4){::bflo(w.x), ::bfhi(w.x), ::bflo(w.y), ::bfhi(w.y)}; b = (f32x4){::bflo(w.z), ::bfhi(w.z), ::bflo(w.w), ::bfhi(w.w)}; }
;     __device__ __forceinline__ void operator()(const f32x4 (&acc)[2][2][4][2], const Unit& u, int wr, int wc, int fr, int fq) const {
;     ...
;                 const size_t r = (size_t)(row0 + ai * HALF + m * 16);
;                 u32x4 gv[2];
; #pragma unroll
;                 for (int bj = 0; bj < 2; ++bj) gv[bj] = *(const u32x4*)(G + r * 3072 + 2048 + col0 + bj * HALF);
; #pragma unroll
;                 for (int bj = 0; bj < 2; ++bj) {
;                     f32x4 g0, g1; unpack8(gv[bj], g0, g1);
;                     f32x4 v0 = acc[ai][bj][m][0], v1 = acc[ai][bj][m][1];
; #pragma unroll
;                     for (int j = 0; j < 4; ++j) { v0[j] *= fmaxf(g0[j], 1e-30f); v1[j] *= fmaxf(g1[j], 1e-30f); }
;                     u32x4 w; w.x = ::pk2(v0[0], v0[1]); w.y = ::pk2(v0[2], v0[3]); w.z = ::pk2(v1[0], v1[1]); w.w = ::pk2(v1[2], v1[3]);
;                     *(u32x4*)(Bo + r * 1024 + col0 + bj * HALF) = w;
;                 }
	v_lshl_add_u64 v[122:123], v[122:123], 0, v[0:1]
	v_lshl_add_u64 v[128:129], s[46:47], 0, v[128:129]
	v_lshl_add_u64 v[130:131], v[122:123], 0, s[54:55]
	v_add_co_u32_e32 v122, vcc, s2, v122
	v_lshl_add_u64 v[128:129], v[128:129], 0, v[0:1]
	s_nop 0
	v_addc_co_u32_e32 v123, vcc, 0, v123, vcc
	v_lshlrev_b32_e32 v3, 16, v124
	v_and_b32_e32 v117, 0xffff0000, v124
	v_lshlrev_b32_e32 v124, 16, v125
	v_and_b32_e32 v125, 0xffff0000, v125
	v_lshlrev_b32_e32 v140, 16, v126
	v_and_b32_e32 v126, 0xffff0000, v126
	v_lshlrev_b32_e32 v141, 16, v127
	v_and_b32_e32 v127, 0xffff0000, v127
	v_lshlrev_b32_e32 v145, 16, v118
	v_and_b32_e32 v118, 0xffff0000, v118
	v_lshlrev_b32_e32 v146, 16, v119
	v_and_b32_e32 v119, 0xffff0000, v119
	v_lshlrev_b32_e32 v147, 16, v120
	v_and_b32_e32 v120, 0xffff0000, v120
	v_lshlrev_b32_e32 v150, 16, v121
	v_and_b32_e32 v121, 0xffff0000, v121
	v_max_f32_e32 v3, v3, v3
	v_max_f32_e32 v140, v140, v140
	v_max_f32_e32 v117, v117, v117
	v_max_f32_e32 v126, v126, v126
	v_max_f32_e32 v124, v124, v124
	v_max_f32_e32 v141, v141, v141
	v_max_f32_e32 v125, v125, v125
	v_max_f32_e32 v127, v127, v127
	v_max_f32_e32 v145, v145, v145
	v_max_f32_e32 v147, v147, v147
	v_max_f32_e32 v151, v118, v118
	v_max_f32_e32 v152, v120, v120
	v_max_f32_e32 v153, v146, v146
	v_max_f32_e32 v154, v150, v150
	v_max_f32_e32 v155, v119, v119
	v_max_f32_e32 v156, v121, v121
	v_max_f32_e32 v118, 0xda24260, v3
	v_max_f32_e32 v120, 0xda24260, v140
	v_max_f32_e32 v119, 0xda24260, v117
	v_max_f32_e32 v121, 0xda24260, v126
	v_max_f32_e32 v124, 0xda24260, v124
	v_max_f32_e32 v126, 0xda24260, v141
	v_max_f32_e32 v125, 0xda24260, v125
	v_max_f32_e32 v127, 0xda24260, v127
	v_max_f32_e32 v140, 0xda24260, v145
	v_max_f32_e32 v146, 0xda24260, v147
	v_max_f32_e32 v141, 0xda24260, v151
	v_max_f32_e32 v147, 0xda24260, v152
	v_max_f32_e32 v150, 0xda24260, v153
	v_max_f32_e32 v152, 0xda24260, v154
	v_max_f32_e32 v151, 0xda24260, v155
	v_max_f32_e32 v153, 0xda24260, v156
	v_pk_mul_f32 v[112:113], v[112:113], v[118:119]
	v_pk_mul_f32 v[118:119], v[108:109], v[120:121]
	v_pk_mul_f32 v[114:115], v[114:115], v[124:125]
	v_pk_mul_f32 v[120:121], v[110:111], v[126:127]
	v_pk_mul_f32 v[104:105], v[104:105], v[140:141]
	v_pk_mul_f32 v[124:125], v[100:101], v[146:147]
	v_cvt_pk_bf16_f32 v108, v112, v113
	v_cvt_pk_bf16_f32 v109, v114, v115
	v_cvt_pk_bf16_f32 v110, v118, v119
	v_cvt_pk_bf16_f32 v111, v120, v121
	v_pk_mul_f32 v[106:107], v[106:107], v[150:151]
	v_pk_mul_f32 v[112:113], v[102:103], v[152:153]
	global_store_dwordx4 v[128:129], v[108:111], off sc1
	v_cvt_pk_bf16_f32 v100, v104, v105
	v_cvt_pk_bf16_f32 v101, v106, v107
	v_cvt_pk_bf16_f32 v102, v124, v125
	v_cvt_pk_bf16_f32 v103, v112, v113
	s_nop 1
	v_mov_b32_e32 v108, v204
	v_mov_b32_e32 v109, v205
	v_mov_b32_e32 v110, v206
	v_mov_b32_e32 v111, v207
	v_ashrrev_i32_e32 v117, 31, v116
	global_store_dwordx4 v[128:129], v[100:103], off offset:256 sc1
	s_nop 1
	v_mov_b32_e32 v102, v208
	v_mov_b32_e32 v103, v209
	v_mov_b32_e32 v104, v210
	v_mov_b32_e32 v105, v211
	v_lshlrev_b64 v[112:113], 11, v[116:117]
	v_or_b32_e32 v100, 48, v144
	v_mad_i64_i32 v[106:107], s[14:15], v100, s4, v[148:149]
	v_lshl_add_u64 v[106:107], v[106:107], 0, v[0:1]
	v_lshl_add_u64 v[112:113], s[46:47], 0, v[112:113]
	v_lshl_add_u64 v[114:115], v[106:107], 0, s[54:55]
	v_add_co_u32_e32 v106, vcc, s2, v106
	v_lshl_add_u64 v[112:113], v[112:113], 0, v[0:1]
	s_nop 0
	v_addc_co_u32_e32 v107, vcc, 0, v107, vcc
	v_lshlrev_b32_e32 v3, 16, v108
	v_and_b32_e32 v101, 0xffff0000, v108
	v_lshlrev_b32_e32 v108, 16, v109
	v_and_b32_e32 v109, 0xffff0000, v109
	v_lshlrev_b32_e32 v116, 16, v110
	v_and_b32_e32 v110, 0xffff0000, v110
	v_lshlrev_b32_e32 v117, 16, v111
	v_and_b32_e32 v111, 0xffff0000, v111
	v_lshlrev_b32_e32 v118, 16, v102
	v_and_b32_e32 v102, 0xffff0000, v102
	v_lshlrev_b32_e32 v119, 16, v103
	v_and_b32_e32 v103, 0xffff0000, v103
	v_lshlrev_b32_e32 v120, 16, v104
	v_and_b32_e32 v104, 0xffff0000, v104
	v_lshlrev_b32_e32 v121, 16, v105
	v_and_b32_e32 v105, 0xffff0000, v105
	v_max_f32_e32 v3, v3, v3
	v_max_f32_e32 v116, v116, v116
	v_max_f32_e32 v101, v101, v101
	v_max_f32_e32 v110, v110, v110
	v_max_f32_e32 v108, v108, v108
	v_max_f32_e32 v117, v117, v117
	v_max_f32_e32 v109, v109, v109
	v_max_f32_e32 v111, v111, v111
	v_max_f32_e32 v118, v118, v118
	v_max_f32_e32 v120, v120, v120
	v_max_f32_e32 v122, v102, v102
	v_max_f32_e32 v123, v104, v104
	v_max_f32_e32 v124, v119, v119
	v_max_f32_e32 v121, v121, v121
	v_max_f32_e32 v125, v103, v103
	v_max_f32_e32 v126, v105, v105
	v_max_f32_e32 v102, 0xda24260, v3
	v_max_f32_e32 v104, 0xda24260, v116
	v_max_f32_e32 v103, 0xda24260, v101
	v_max_f32_e32 v105, 0xda24260, v110
	v_max_f32_e32 v108, 0xda24260, v108
	v_max_f32_e32 v110, 0xda24260, v117
	v_max_f32_e32 v109, 0xda24260, v109
	v_max_f32_e32 v111, 0xda24260, v111
	v_max_f32_e32 v116, 0xda24260, v118
	v_max_f32_e32 v118, 0xda24260, v120
	v_max_f32_e32 v117, 0xda24260, v122
	v_max_f32_e32 v119, 0xda24260, v123
	v_max_f32_e32 v120, 0xda24260, v124
	v_max_f32_e32 v122, 0xda24260, v121
	v_max_f32_e32 v121, 0xda24260, v125
	v_max_f32_e32 v123, 0xda24260, v126
	v_pk_mul_f32 v[96:97], v[96:97], v[102:103]
	v_pk_mul_f32 v[102:103], v[92:93], v[104:105]
	v_pk_mul_f32 v[98:99], v[98:99], v[108:109]
	v_pk_mul_f32 v[104:105], v[94:95], v[110:111]
	v_pk_mul_f32 v[88:89], v[88:89], v[116:117]
	v_pk_mul_f32 v[108:109], v[84:85], v[118:119]
	v_cvt_pk_bf16_f32 v92, v96, v97
	v_cvt_pk_bf16_f32 v93, v98, v99
	v_cvt_pk_bf16_f32 v94, v102, v103
	v_cvt_pk_bf16_f32 v95, v104, v105
	v_pk_mul_f32 v[90:91], v[90:91], v[120:121]
	v_pk_mul_f32 v[96:97], v[86:87], v[122:123]
; __device__ __forceinline__ unsigned pk2(float lo, float hi) { f32x2 v = {lo, hi}; bf16x2_t b = __builtin_convertvector(v, bf16x2_t); return __builtin_bit_cast(unsigned, b); }
;     static __device__ __forceinline__ void unpack8(u32x4 w, f32x4& a, f32x4& b) { a = (f32x4){::bflo(w.x), ::bfhi(w.x), ::bflo(w.y), ::bfhi(w.y)}; b = (f32x4){::bflo(w.z), ::bfhi(w.z), ::bflo(w.w), ::bfhi(w.w)}; }
;     __device__ __forceinline__ void operator()(const f32x4 (&acc)[2][2][4][2], const Unit& u, int wr, int wc, int fr, int fq) const {
;     ...
;                 const size_t r = (size_t)(row0 + ai * HALF + m * 16);
;                 u32x4 gv[2];
; #pragma unroll
;                 for (int bj = 0; bj < 2; ++bj) gv[bj] = *(const u32x4*)(G + r * 3072 + 2048 + col0 + bj * HALF);
; #pragma unroll
;                 for (int bj = 0; bj < 2; ++bj) {
;                     f32x4 g0, g1; unpack8(gv[bj], g0, g1);
;                     f32x4 v0 = acc[ai][bj][m][0], v1 = acc[ai][bj][m][1];
; #pragma unroll
;                     for (int j = 0; j < 4; ++j) { v0[j] *= fmaxf(g0[j], 1e-30f); v1[j] *= fmaxf(g1[j], 1e-30f); }
;                     u32x4 w; w.x = ::pk2(v0[0], v0[1]); w.y = ::pk2(v0[2], v0[3]); w.z = ::pk2(v1[0], v1[1]); w.w = ::pk2(v1[2], v1[3]);
;                     *(u32x4*)(Bo + r * 1024 + col0 + bj * HALF) = w;
;                 }
	global_store_dwordx4 v[112:113], v[92:95], off sc1
	v_cvt_pk_bf16_f32 v84, v88, v89
	v_cvt_pk_bf16_f32 v85, v90, v91
	v_cvt_pk_bf16_f32 v86, v108, v109
	v_cvt_pk_bf16_f32 v87, v96, v97
	s_nop 1
	v_mov_b32_e32 v92, v212
	v_mov_b32_e32 v93, v213
	v_mov_b32_e32 v94, v214
	v_mov_b32_e32 v95, v215
	v_ashrrev_i32_e32 v101, 31, v100
	global_store_dwordx4 v[112:113], v[84:87], off offset:256 sc1
	s_nop 1
	v_mov_b32_e32 v86, v216
	v_mov_b32_e32 v87, v217
	v_mov_b32_e32 v88, v218
	v_mov_b32_e32 v89, v219
	v_lshlrev_b64 v[96:97], 11, v[100:101]
	v_add_u32_e32 v84, 0x80, v144
	v_mad_i64_i32 v[90:91], s[14:15], v84, s4, v[148:149]
	v_lshl_add_u64 v[90:91], v[90:91], 0, v[0:1]
	v_lshl_add_u64 v[96:97], s[46:47], 0, v[96:97]
	v_lshl_add_u64 v[98:99], v[90:91], 0, s[54:55]
	v_add_co_u32_e32 v90, vcc, s2, v90
	v_lshl_add_u64 v[96:97], v[96:97], 0, v[0:1]
	s_nop 0
	v_addc_co_u32_e32 v91, vcc, 0, v91, vcc
	v_lshlrev_b32_e32 v3, 16, v92
	v_and_b32_e32 v85, 0xffff0000, v92
	v_lshlrev_b32_e32 v92, 16, v93
	v_and_b32_e32 v93, 0xffff0000, v93
	v_lshlrev_b32_e32 v100, 16, v94
	v_and_b32_e32 v94, 0xffff0000, v94
	v_lshlrev_b32_e32 v101, 16, v95
	v_and_b32_e32 v95, 0xffff0000, v95
	v_lshlrev_b32_e32 v102, 16, v86
	v_and_b32_e32 v86, 0xffff0000, v86
	v_lshlrev_b32_e32 v103, 16, v87
	v_and_b32_e32 v87, 0xffff0000, v87
	v_lshlrev_b32_e32 v104, 16, v88
	v_and_b32_e32 v88, 0xffff0000, v88
	v_lshlrev_b32_e32 v105, 16, v89
	v_and_b32_e32 v89, 0xffff0000, v89
	v_max_f32_e32 v3, v3, v3
	v_max_f32_e32 v100, v100, v100
	v_max_f32_e32 v85, v85, v85
	v_max_f32_e32 v94, v94, v94
	v_max_f32_e32 v92, v92, v92
	v_max_f32_e32 v101, v101, v101
	v_max_f32_e32 v93, v93, v93
	v_max_f32_e32 v95, v95, v95
	v_max_f32_e32 v102, v102, v102
	v_max_f32_e32 v104, v104, v104
	v_max_f32_e32 v106, v86, v86
	v_max_f32_e32 v107, v88, v88
	v_max_f32_e32 v108, v103, v103
	v_max_f32_e32 v105, v105, v105
	v_max_f32_e32 v109, v87, v87
	v_max_f32_e32 v110, v89, v89
	v_max_f32_e32 v86, 0xda24260, v3
	v_max_f32_e32 v88, 0xda24260, v100
	v_max_f32_e32 v87, 0xda24260, v85
	v_max_f32_e32 v89, 0xda24260, v94
	v_max_f32_e32 v92, 0xda24260, v92
	v_max_f32_e32 v94, 0xda24260, v101
	v_max_f32_e32 v93, 0xda24260, v93
	v_max_f32_e32 v95, 0xda24260, v95
	v_max_f32_e32 v100, 0xda24260, v102
	v_max_f32_e32 v102, 0xda24260, v104
	v_max_f32_e32 v101, 0xda24260, v106
	v_max_f32_e32 v103, 0xda24260, v107
	v_max_f32_e32 v104, 0xda24260, v108
	v_max_f32_e32 v106, 0xda24260, v105
	v_max_f32_e32 v105, 0xda24260, v109
	v_max_f32_e32 v107, 0xda24260, v110
	v_pk_mul_f32 v[80:81], v[80:81], v[86:87]
	v_pk_mul_f32 v[86:87], v[76:77], v[88:89]
	v_pk_mul_f32 v[82:83], v[82:83], v[92:93]
	v_pk_mul_f32 v[88:89], v[78:79], v[94:95]
	v_pk_mul_f32 v[72:73], v[72:73], v[100:101]
	v_pk_mul_f32 v[92:93], v[68:69], v[102:103]
	v_cvt_pk_bf16_f32 v76, v80, v81
	v_cvt_pk_bf16_f32 v77, v82, v83
	v_cvt_pk_bf16_f32 v78, v86, v87
	v_cvt_pk_bf16_f32 v79, v88, v89
	v_pk_mul_f32 v[74:75], v[74:75], v[104:105]
	v_pk_mul_f32 v[80:81], v[70:71], v[106:107]
	global_store_dwordx4 v[96:97], v[76:79], off sc1
	v_cvt_pk_bf16_f32 v68, v72, v73
	v_cvt_pk_bf16_f32 v69, v74, v75
	v_cvt_pk_bf16_f32 v70, v92, v93
	v_cvt_pk_bf16_f32 v71, v80, v81
	s_nop 1
	v_mov_b32_e32 v76, v220
	v_mov_b32_e32 v77, v221
	v_mov_b32_e32 v78, v222
	v_mov_b32_e32 v79, v223
	v_ashrrev_i32_e32 v85, 31, v84
	global_store_dwordx4 v[96:97], v[68:71], off offset:256 sc1
	s_nop 1
	v_mov_b32_e32 v70, v224
	v_mov_b32_e32 v71, v225
	v_mov_b32_e32 v72, v226
	v_mov_b32_e32 v73, v227
	v_lshlrev_b64 v[80:81], 11, v[84:85]
	v_add_u32_e32 v68, 0x90, v144
	v_mad_i64_i32 v[74:75], s[14:15], v68, s4, v[148:149]
	v_lshl_add_u64 v[74:75], v[74:75], 0, v[0:1]
	v_lshl_add_u64 v[80:81], s[46:47], 0, v[80:81]
	v_lshl_add_u64 v[82:83], v[74:75], 0, s[54:55]
	v_add_co_u32_e32 v74, vcc, s2, v74
	v_lshl_add_u64 v[80:81], v[80:81], 0, v[0:1]
	s_nop 0
	v_addc_co_u32_e32 v75, vcc, 0, v75, vcc
	v_lshlrev_b32_e32 v3, 16, v76
	v_and_b32_e32 v69, 0xffff0000, v76
	v_lshlrev_b32_e32 v76, 16, v77
	v_and_b32_e32 v77, 0xffff0000, v77
	v_lshlrev_b32_e32 v84, 16, v78
	v_and_b32_e32 v78, 0xffff0000, v78
	v_lshlrev_b32_e32 v85, 16, v79
	v_and_b32_e32 v79, 0xffff0000, v79
	v_lshlrev_b32_e32 v86, 16, v70
	v_and_b32_e32 v70, 0xffff0000, v70
	v_lshlrev_b32_e32 v87, 16, v71
	v_and_b32_e32 v71, 0xffff0000, v71
	v_lshlrev_b32_e32 v88, 16, v72
	v_and_b32_e32 v72, 0xffff0000, v72
	v_lshlrev_b32_e32 v89, 16, v73
	v_and_b32_e32 v73, 0xffff0000, v73
	v_max_f32_e32 v3, v3, v3
	v_max_f32_e32 v84, v84, v84
	v_max_f32_e32 v69, v69, v69
	v_max_f32_e32 v78, v78, v78
	v_max_f32_e32 v76, v76, v76
	v_max_f32_e32 v85, v85, v85
	v_max_f32_e32 v77, v77, v77
	v_max_f32_e32 v79, v79, v79
	v_max_f32_e32 v86, v86, v86
	v_max_f32_e32 v88, v88, v88
	v_max_f32_e32 v90, v70, v70
	v_max_f32_e32 v91, v72, v72
	v_max_f32_e32 v92, v87, v87
	v_max_f32_e32 v89, v89, v89
	v_max_f32_e32 v93, v71, v71
	v_max_f32_e32 v94, v73, v73
	v_max_f32_e32 v70, 0xda24260, v3
	v_max_f32_e32 v72, 0xda24260, v84
	v_max_f32_e32 v71, 0xda24260, v69
	v_max_f32_e32 v73, 0xda24260, v78
	v_max_f32_e32 v76, 0xda24260, v76
	v_max_f32_e32 v78, 0xda24260, v85
	v_max_f32_e32 v77, 0xda24260, v77
	v_max_f32_e32 v79, 0xda24260, v79
	v_max_f32_e32 v84, 0xda24260, v86
	v_max_f32_e32 v86, 0xda24260, v88
	v_max_f32_e32 v85, 0xda24260, v90
	v_max_f32_e32 v87, 0xda24260, v91
	v_max_f32_e32 v88, 0xda24260, v92
	v_max_f32_e32 v90, 0xda24260, v89
	v_max_f32_e32 v89, 0xda24260, v93
	v_max_f32_e32 v91, 0xda24260, v94
	v_pk_mul_f32 v[64:65], v[64:65], v[70:71]
	v_pk_mul_f32 v[70:71], v[60:61], v[72:73]
	v_pk_mul_f32 v[66:67], v[66:67], v[76:77]
	v_pk_mul_f32 v[72:73], v[62:63], v[78:79]
; __device__ __forceinline__ unsigned pk2(float lo, float hi) { f32x2 v = {lo, hi}; bf16x2_t b = __builtin_convertvector(v, bf16x2_t); return __builtin_bit_cast(unsigned, b); }
;     static __device__ __forceinline__ void unpack8(u32x4 w, f32x4& a, f32x4& b) { a = (f32x4){::bflo(w.x), ::bfhi(w.x), ::bflo(w.y), ::bfhi(w.y)}; b = (f32x4){::bflo(w.z), ::bfhi(w.z), ::bflo(w.w), ::bfhi(w.w)}; }
;     __device__ __forceinline__ void operator()(const f32x4 (&acc)[2][2][4][2], const Unit& u, int wr, int wc, int fr, int fq) const {
;         const int row0 = u.pm * BM + wr * 64 + fr, col0 = u.pn * BM + wc * 32 + 8 * fq;
; #pragma unroll
;         for (int ai = 0; ai < 2; ++ai)
; #pragma unroll
;             for (int m = 0; m < 4; ++m) {
;                 const size_t r = (size_t)(row0 + ai * HALF + m * 16);
;                 u32x4 gv[2];
; #pragma unroll
;                 for (int bj = 0; bj < 2; ++bj) gv[bj] = *(const u32x4*)(G + r * 3072 + 2048 + col0 + bj * HALF);
; #pragma unroll
;                 for (int bj = 0; bj < 2; ++bj) {
;                     f32x4 g0, g1; unpack8(gv[bj], g0, g1);
;                     f32x4 v0 = acc[ai][bj][m][0], v1 = acc[ai][bj][m][1];
; #pragma unroll
;                     for (int j = 0; j < 4; ++j) { v0[j] *= fmaxf(g0[j], 1e-30f); v1[j] *= fmaxf(g1[j], 1e-30f); }
;                     u32x4 w; w.x = ::pk2(v0[0], v0[1]); w.y = ::pk2(v0[2], v0[3]); w.z = ::pk2(v1[0], v1[1]); w.w = ::pk2(v1[2], v1[3]);
;                     *(u32x4*)(Bo + r * 1024 + col0 + bj * HALF) = w;
;                 }
;             }
;     }
	v_pk_mul_f32 v[56:57], v[56:57], v[84:85]
	v_pk_mul_f32 v[76:77], v[52:53], v[86:87]
	v_cvt_pk_bf16_f32 v60, v64, v65
	v_cvt_pk_bf16_f32 v61, v66, v67
	v_cvt_pk_bf16_f32 v62, v70, v71
	v_cvt_pk_bf16_f32 v63, v72, v73
	v_pk_mul_f32 v[58:59], v[58:59], v[88:89]
	v_pk_mul_f32 v[64:65], v[54:55], v[90:91]
	global_store_dwordx4 v[80:81], v[60:63], off sc1
	v_cvt_pk_bf16_f32 v52, v56, v57
	v_cvt_pk_bf16_f32 v53, v58, v59
	v_cvt_pk_bf16_f32 v54, v76, v77
	v_cvt_pk_bf16_f32 v55, v64, v65
	s_nop 1
	v_mov_b32_e32 v60, v228
	v_mov_b32_e32 v61, v229
	v_mov_b32_e32 v62, v230
	v_mov_b32_e32 v63, v231
	v_ashrrev_i32_e32 v69, 31, v68
	global_store_dwordx4 v[80:81], v[52:55], off offset:256 sc1
	s_nop 1
	v_mov_b32_e32 v54, v232
	v_mov_b32_e32 v55, v233
	v_mov_b32_e32 v56, v234
	v_mov_b32_e32 v57, v235
	v_lshlrev_b64 v[64:65], 11, v[68:69]
	v_add_u32_e32 v52, 0xa0, v144
	v_mad_i64_i32 v[58:59], s[14:15], v52, s4, v[148:149]
	v_lshl_add_u64 v[58:59], v[58:59], 0, v[0:1]
	v_lshl_add_u64 v[64:65], s[46:47], 0, v[64:65]
	v_lshl_add_u64 v[66:67], v[58:59], 0, s[54:55]
	v_add_co_u32_e32 v58, vcc, s2, v58
	v_lshl_add_u64 v[64:65], v[64:65], 0, v[0:1]
	s_nop 0
	v_addc_co_u32_e32 v59, vcc, 0, v59, vcc
	v_lshlrev_b32_e32 v3, 16, v60
	v_and_b32_e32 v53, 0xffff0000, v60
	v_lshlrev_b32_e32 v60, 16, v61
	v_and_b32_e32 v61, 0xffff0000, v61
	v_lshlrev_b32_e32 v68, 16, v62
	v_and_b32_e32 v62, 0xffff0000, v62
	v_lshlrev_b32_e32 v69, 16, v63
	v_and_b32_e32 v63, 0xffff0000, v63
	v_lshlrev_b32_e32 v70, 16, v54
	v_and_b32_e32 v54, 0xffff0000, v54
	v_lshlrev_b32_e32 v71, 16, v55
	v_and_b32_e32 v55, 0xffff0000, v55
	v_lshlrev_b32_e32 v72, 16, v56
	v_and_b32_e32 v56, 0xffff0000, v56
	v_lshlrev_b32_e32 v73, 16, v57
	v_and_b32_e32 v57, 0xffff0000, v57
	v_max_f32_e32 v3, v3, v3
	v_max_f32_e32 v68, v68, v68
	v_max_f32_e32 v53, v53, v53
	v_max_f32_e32 v62, v62, v62
	v_max_f32_e32 v60, v60, v60
	v_max_f32_e32 v69, v69, v69
	v_max_f32_e32 v61, v61, v61
	v_max_f32_e32 v63, v63, v63
	v_max_f32_e32 v70, v70, v70
	v_max_f32_e32 v72, v72, v72
	v_max_f32_e32 v74, v54, v54
	v_max_f32_e32 v75, v56, v56
	v_max_f32_e32 v76, v71, v71
	v_max_f32_e32 v73, v73, v73
	v_max_f32_e32 v77, v55, v55
	v_max_f32_e32 v78, v57, v57
	v_max_f32_e32 v54, 0xda24260, v3
	v_max_f32_e32 v56, 0xda24260, v68
	v_max_f32_e32 v55, 0xda24260, v53
	v_max_f32_e32 v57, 0xda24260, v62
	v_max_f32_e32 v60, 0xda24260, v60
	v_max_f32_e32 v62, 0xda24260, v69
	v_max_f32_e32 v61, 0xda24260, v61
	v_max_f32_e32 v63, 0xda24260, v63
	v_max_f32_e32 v68, 0xda24260, v70
	v_max_f32_e32 v70, 0xda24260, v72
	v_max_f32_e32 v69, 0xda24260, v74
	v_max_f32_e32 v71, 0xda24260, v75
	v_max_f32_e32 v72, 0xda24260, v76
	v_max_f32_e32 v74, 0xda24260, v73
	v_max_f32_e32 v73, 0xda24260, v77
	v_max_f32_e32 v75, 0xda24260, v78
	v_pk_mul_f32 v[48:49], v[48:49], v[54:55]
	v_pk_mul_f32 v[54:55], v[44:45], v[56:57]
	v_pk_mul_f32 v[50:51], v[50:51], v[60:61]
	v_pk_mul_f32 v[56:57], v[46:47], v[62:63]
	v_pk_mul_f32 v[40:41], v[40:41], v[68:69]
	v_pk_mul_f32 v[60:61], v[36:37], v[70:71]
	v_cvt_pk_bf16_f32 v44, v48, v49
	v_cvt_pk_bf16_f32 v45, v50, v51
	v_cvt_pk_bf16_f32 v46, v54, v55
	v_cvt_pk_bf16_f32 v47, v56, v57
	v_pk_mul_f32 v[42:43], v[42:43], v[72:73]
	v_pk_mul_f32 v[48:49], v[38:39], v[74:75]
	global_store_dwordx4 v[64:65], v[44:47], off sc1
	v_cvt_pk_bf16_f32 v36, v40, v41
	v_cvt_pk_bf16_f32 v37, v42, v43
	v_cvt_pk_bf16_f32 v38, v60, v61
	v_cvt_pk_bf16_f32 v39, v48, v49
	s_nop 1
	v_mov_b32_e32 v44, v240
	v_mov_b32_e32 v45, v241
	v_mov_b32_e32 v46, v242
	v_mov_b32_e32 v47, v243
	v_ashrrev_i32_e32 v53, 31, v52
	global_store_dwordx4 v[64:65], v[36:39], off offset:256 sc1
	s_nop 1
	v_mov_b32_e32 v38, v244
	v_mov_b32_e32 v39, v245
	v_mov_b32_e32 v40, v246
	v_mov_b32_e32 v41, v247
	v_lshlrev_b64 v[48:49], 11, v[52:53]
	v_add_u32_e32 v36, 0xb0, v144
	v_mad_i64_i32 v[42:43], s[14:15], v36, s4, v[148:149]
	v_lshl_add_u64 v[42:43], v[42:43], 0, v[0:1]
	v_lshl_add_u64 v[48:49], s[46:47], 0, v[48:49]
	v_lshl_add_u64 v[50:51], v[42:43], 0, s[54:55]
	v_add_co_u32_e32 v42, vcc, s2, v42
	v_lshl_add_u64 v[48:49], v[48:49], 0, v[0:1]
	s_nop 0
	v_addc_co_u32_e32 v43, vcc, 0, v43, vcc
	s_and_b64 vcc, exec, s[40:41]
	s_mov_b64 s[40:41], -1
	v_lshlrev_b32_e32 v3, 16, v44
	v_and_b32_e32 v37, 0xffff0000, v44
	v_lshlrev_b32_e32 v44, 16, v45
	v_and_b32_e32 v45, 0xffff0000, v45
	v_lshlrev_b32_e32 v52, 16, v46
	v_and_b32_e32 v46, 0xffff0000, v46
	v_lshlrev_b32_e32 v53, 16, v47
	v_and_b32_e32 v47, 0xffff0000, v47
	v_lshlrev_b32_e32 v54, 16, v38
	v_and_b32_e32 v38, 0xffff0000, v38
	v_lshlrev_b32_e32 v55, 16, v39
	v_and_b32_e32 v39, 0xffff0000, v39
	v_lshlrev_b32_e32 v56, 16, v40
	v_and_b32_e32 v40, 0xffff0000, v40
	v_lshlrev_b32_e32 v57, 16, v41
	v_and_b32_e32 v41, 0xffff0000, v41
	v_max_f32_e32 v3, v3, v3
	v_max_f32_e32 v52, v52, v52
	v_max_f32_e32 v37, v37, v37
	v_max_f32_e32 v46, v46, v46
	v_max_f32_e32 v44, v44, v44
	v_max_f32_e32 v53, v53, v53
	v_max_f32_e32 v45, v45, v45
	v_max_f32_e32 v47, v47, v47
	v_max_f32_e32 v54, v54, v54
	v_max_f32_e32 v56, v56, v56
	v_max_f32_e32 v58, v38, v38
	v_max_f32_e32 v59, v40, v40
	v_max_f32_e32 v60, v55, v55
	v_max_f32_e32 v57, v57, v57
	v_max_f32_e32 v61, v39, v39
	v_max_f32_e32 v62, v41, v41
	v_max_f32_e32 v38, 0xda24260, v3
	v_max_f32_e32 v40, 0xda24260, v52
	v_max_f32_e32 v39, 0xda24260, v37
	v_max_f32_e32 v41, 0xda24260, v46
	v_max_f32_e32 v44, 0xda24260, v44
	v_max_f32_e32 v46, 0xda24260, v53
	v_max_f32_e32 v45, 0xda24260, v45
	v_max_f32_e32 v47, 0xda24260, v47
	v_max_f32_e32 v52, 0xda24260, v54
	v_max_f32_e32 v54, 0xda24260, v56
	v_max_f32_e32 v53, 0xda24260, v58
	v_max_f32_e32 v55, 0xda24260, v59
	v_max_f32_e32 v56, 0xda24260, v60
	v_max_f32_e32 v58, 0xda24260, v57
	v_max_f32_e32 v57, 0xda24260, v61
	v_max_f32_e32 v59, 0xda24260, v62
	v_pk_mul_f32 v[32:33], v[32:33], v[38:39]
	v_pk_mul_f32 v[38:39], v[28:29], v[40:41]
	v_pk_mul_f32 v[34:35], v[34:35], v[44:45]
	v_pk_mul_f32 v[40:41], v[30:31], v[46:47]
	v_pk_mul_f32 v[24:25], v[24:25], v[52:53]
	v_pk_mul_f32 v[44:45], v[20:21], v[54:55]
	v_cvt_pk_bf16_f32 v28, v32, v33
	v_cvt_pk_bf16_f32 v29, v34, v35
	v_cvt_pk_bf16_f32 v30, v38, v39
	v_cvt_pk_bf16_f32 v31, v40, v41
	v_pk_mul_f32 v[26:27], v[26:27], v[56:57]
	v_pk_mul_f32 v[32:33], v[22:23], v[58:59]
	global_store_dwordx4 v[48:49], v[28:31], off sc1
	v_cvt_pk_bf16_f32 v20, v24, v25
	v_cvt_pk_bf16_f32 v21, v26, v27
	v_cvt_pk_bf16_f32 v22, v44, v45
	v_cvt_pk_bf16_f32 v23, v32, v33
	global_load_dwordx4 v[28:31], v[42:43], off
	v_ashrrev_i32_e32 v37, 31, v36
	global_store_dwordx4 v[48:49], v[20:23], off offset:256 sc1
	global_load_dwordx4 v[20:23], v[50:51], off offset:256
	v_lshlrev_b64 v[24:25], 11, v[36:37]
	v_lshl_add_u64 v[24:25], s[46:47], 0, v[24:25]
	v_lshl_add_u64 v[0:1], v[24:25], 0, v[0:1]
	s_waitcnt vmcnt(2)
; __device__ __forceinline__ unsigned pk2(float lo, float hi) { f32x2 v = {lo, hi}; bf16x2_t b = __builtin_convertvector(v, bf16x2_t); return __builtin_bit_cast(unsigned, b); }
;     static __device__ __forceinline__ void unpack8(u32x4 w, f32x4& a, f32x4& b) { a = (f32x4){::bflo(w.x), ::bfhi(w.x), ::bflo(w.y), ::bfhi(w.y)}; b = (f32x4){::bflo(w.z), ::bfhi(w.z), ::bflo(w.w), ::bfhi(w.w)}; }
; #define PG8_BAR __builtin_amdgcn_s_barrier()
;     __device__ __forceinline__ void operator()(const f32x4 (&acc)[2][2][4][2], const Unit& u, int wr, int wc, int fr, int fq) const {
;     ...
;                 const size_t r = (size_t)(row0 + ai * HALF + m * 16);
;                 u32x4 gv[2];
; #pragma unroll
;                 for (int bj = 0; bj < 2; ++bj) gv[bj] = *(const u32x4*)(G + r * 3072 + 2048 + col0 + bj * HALF);
; #pragma unroll
;                 for (int bj = 0; bj < 2; ++bj) {
;                     f32x4 g0, g1; unpack8(gv[bj], g0, g1);
;                     f32x4 v0 = acc[ai][bj][m][0], v1 = acc[ai][bj][m][1];
; #pragma unroll
;                     for (int j = 0; j < 4; ++j) { v0[j] *= fmaxf(g0[j], 1e-30f); v1[j] *= fmaxf(g1[j], 1e-30f); }
;                     u32x4 w; w.x = ::pk2(v0[0], v0[1]); w.y = ::pk2(v0[2], v0[3]); w.z = ::pk2(v1[0], v1[1]); w.w = ::pk2(v1[2], v1[3]);
;                     *(u32x4*)(Bo + r * 1024 + col0 + bj * HALF) = w;
;                 }
;             }
;     }
; template <class Epi, class Sched, bool ALIGN_EPI = false, bool SP2 = false>
; __device__ __forceinline__ void gemm_phase(PG8_LAS unsigned char* lds, const Gemm g, const Sched& S, const Epi& E) {
;     ...
;         cur = nxt; cA = nA; cB = nB; ++ui;
;         if constexpr (ALIGN_EPI) { if (wr == 1) PG8_BAR; }
	v_lshlrev_b32_e32 v3, 16, v28
	v_and_b32_e32 v24, 0xffff0000, v28
	v_lshlrev_b32_e32 v25, 16, v29
	v_and_b32_e32 v26, 0xffff0000, v29
	v_lshlrev_b32_e32 v27, 16, v30
	v_and_b32_e32 v28, 0xffff0000, v30
	v_lshlrev_b32_e32 v29, 16, v31
	v_and_b32_e32 v30, 0xffff0000, v31
	s_waitcnt vmcnt(0)
	v_lshlrev_b32_e32 v31, 16, v20
	v_and_b32_e32 v20, 0xffff0000, v20
	v_lshlrev_b32_e32 v32, 16, v21
	v_and_b32_e32 v21, 0xffff0000, v21
	v_lshlrev_b32_e32 v33, 16, v22
	v_and_b32_e32 v22, 0xffff0000, v22
	v_lshlrev_b32_e32 v34, 16, v23
	v_and_b32_e32 v23, 0xffff0000, v23
	v_max_f32_e32 v3, v3, v3
	v_max_f32_e32 v27, v27, v27
	v_max_f32_e32 v24, v24, v24
	v_max_f32_e32 v28, v28, v28
	v_max_f32_e32 v25, v25, v25
	v_max_f32_e32 v29, v29, v29
	v_max_f32_e32 v35, v26, v26
	v_max_f32_e32 v30, v30, v30
	v_max_f32_e32 v31, v31, v31
	v_max_f32_e32 v33, v33, v33
	v_max_f32_e32 v36, v20, v20
	v_max_f32_e32 v37, v22, v22
	v_max_f32_e32 v32, v32, v32
	v_max_f32_e32 v34, v34, v34
	v_max_f32_e32 v38, v21, v21
	v_max_f32_e32 v39, v23, v23
	v_max_f32_e32 v20, 0xda24260, v3
	v_max_f32_e32 v22, 0xda24260, v27
	v_max_f32_e32 v21, 0xda24260, v24
	v_max_f32_e32 v23, 0xda24260, v28
	v_max_f32_e32 v24, 0xda24260, v25
	v_max_f32_e32 v26, 0xda24260, v29
	v_max_f32_e32 v25, 0xda24260, v35
	v_max_f32_e32 v27, 0xda24260, v30
	v_max_f32_e32 v28, 0xda24260, v31
	v_max_f32_e32 v30, 0xda24260, v33
	v_max_f32_e32 v29, 0xda24260, v36
	v_max_f32_e32 v31, 0xda24260, v37
	v_max_f32_e32 v32, 0xda24260, v32
	v_max_f32_e32 v34, 0xda24260, v34
	v_max_f32_e32 v33, 0xda24260, v38
	v_max_f32_e32 v35, 0xda24260, v39
	v_pk_mul_f32 v[16:17], v[16:17], v[20:21]
	v_pk_mul_f32 v[12:13], v[12:13], v[22:23]
	v_pk_mul_f32 v[18:19], v[18:19], v[24:25]
	v_pk_mul_f32 v[14:15], v[14:15], v[26:27]
	v_pk_mul_f32 v[8:9], v[8:9], v[28:29]
	v_pk_mul_f32 v[20:21], v[4:5], v[30:31]
	v_pk_mul_f32 v[10:11], v[10:11], v[32:33]
	v_pk_mul_f32 v[22:23], v[6:7], v[34:35]
	v_cvt_pk_bf16_f32 v4, v16, v17
	v_cvt_pk_bf16_f32 v5, v18, v19
	v_cvt_pk_bf16_f32 v6, v12, v13
	v_cvt_pk_bf16_f32 v7, v14, v15
	v_cvt_pk_bf16_f32 v8, v8, v9
	v_cvt_pk_bf16_f32 v9, v10, v11
	v_cvt_pk_bf16_f32 v10, v20, v21
	v_cvt_pk_bf16_f32 v11, v22, v23
	global_store_dwordx4 v[0:1], v[4:7], off sc1
	global_store_dwordx4 v[0:1], v[8:11], off offset:256 sc1
	s_cbranch_vccnz .LBB0_122
	s_andn2_b64 vcc, exec, s[48:49]
	s_cbranch_vccnz .LBB0_121
	s_barrier
	s_branch .LBB0_121
